# P10 epilogue rewritten by hand with packed-f32 pairs (same ops and order per element), scale loads hoisted to the top of the unit
# baseline (speedup 1.0000x reference)
.LBB0_714:
	s_ashr_i32 s35, s34, 31
	s_lshl_b64 s[20:21], s[34:35], 18
	s_add_u32 s36, s2, s20
	s_addc_u32 s37, s3, s21
	s_ashr_i32 s31, s30, 31
	s_lshl_b64 s[20:21], s[30:31], 18
	s_add_u32 s38, s16, s20
	s_addc_u32 s39, s17, s21
	v_lshl_or_b32 v224, s57, 8, v169
	v_lshl_add_u32 v223, s40, 8, v165
	v_lshlrev_b32_e32 v224, 2, v224
	v_lshlrev_b32_e32 v252, 2, v223
	global_load_dwordx4 v[228:231], v224, s[14:15]
	global_load_dwordx4 v[232:235], v224, s[14:15] offset:64
	global_load_dwordx4 v[236:239], v224, s[14:15] offset:512
	global_load_dwordx4 v[240:243], v224, s[14:15] offset:576
	global_load_dword v244, v252, s[12:13]
	global_load_dword v245, v252, s[12:13] offset:64
	global_load_dword v246, v252, s[12:13] offset:128
	global_load_dword v247, v252, s[12:13] offset:192
	global_load_dword v248, v252, s[12:13] offset:512
	global_load_dword v249, v252, s[12:13] offset:576
	global_load_dword v250, v252, s[12:13] offset:640
	global_load_dword v251, v252, s[12:13] offset:704
	s_and_b64 vcc, exec, s[6:7]
	s_cbranch_vccz .Lzskip_P10
	v_mov_b32_e32 v163, 0
	v_mov_b32_e32 v162, 0
	v_mov_b32_e32 v161, 0
	v_mov_b32_e32 v160, 0
	v_mov_b32_e32 v159, 0
	v_mov_b32_e32 v158, 0
	v_mov_b32_e32 v147, 0
	v_mov_b32_e32 v146, 0
	v_mov_b32_e32 v157, 0
	v_mov_b32_e32 v156, 0
	v_mov_b32_e32 v145, 0
	v_mov_b32_e32 v144, 0
	v_mov_b32_e32 v155, 0
	v_mov_b32_e32 v154, 0
	v_mov_b32_e32 v141, 0
	v_mov_b32_e32 v140, 0
	v_mov_b32_e32 v153, 0
	v_mov_b32_e32 v152, 0
	v_mov_b32_e32 v127, 0
	v_mov_b32_e32 v126, 0
	v_mov_b32_e32 v151, 0
	v_mov_b32_e32 v150, 0
	v_mov_b32_e32 v125, 0
	v_mov_b32_e32 v124, 0
	v_mov_b32_e32 v149, 0
	v_mov_b32_e32 v148, 0
	v_mov_b32_e32 v123, 0
	v_mov_b32_e32 v122, 0
	v_mov_b32_e32 v143, 0
	v_mov_b32_e32 v142, 0
	v_mov_b32_e32 v119, 0
	v_mov_b32_e32 v118, 0
	v_mov_b32_e32 v121, 0
	v_mov_b32_e32 v120, 0
	v_mov_b32_e32 v101, 0
	v_mov_b32_e32 v100, 0
	v_mov_b32_e32 v117, 0
	v_mov_b32_e32 v116, 0
	v_mov_b32_e32 v99, 0
	v_mov_b32_e32 v98, 0
	v_mov_b32_e32 v115, 0
	v_mov_b32_e32 v114, 0
	v_mov_b32_e32 v97, 0
	v_mov_b32_e32 v96, 0
	v_mov_b32_e32 v113, 0
	v_mov_b32_e32 v112, 0
	v_mov_b32_e32 v95, 0
	v_mov_b32_e32 v94, 0
	v_mov_b32_e32 v111, 0
	v_mov_b32_e32 v110, 0
	v_mov_b32_e32 v93, 0
	v_mov_b32_e32 v92, 0
	v_mov_b32_e32 v109, 0
	v_mov_b32_e32 v108, 0
	v_mov_b32_e32 v91, 0
	v_mov_b32_e32 v90, 0
	v_mov_b32_e32 v107, 0
	v_mov_b32_e32 v106, 0
	v_mov_b32_e32 v89, 0
	v_mov_b32_e32 v88, 0
	v_mov_b32_e32 v105, 0
	v_mov_b32_e32 v104, 0
	v_mov_b32_e32 v87, 0
	v_mov_b32_e32 v86, 0
	v_mov_b32_e32 v103, 0
	v_mov_b32_e32 v102, 0
	v_mov_b32_e32 v85, 0
	v_mov_b32_e32 v84, 0
	v_mov_b32_e32 v83, 0
	v_mov_b32_e32 v82, 0
	v_mov_b32_e32 v73, 0
	v_mov_b32_e32 v72, 0
	v_mov_b32_e32 v81, 0
	v_mov_b32_e32 v80, 0
	v_mov_b32_e32 v71, 0
	v_mov_b32_e32 v70, 0
	v_mov_b32_e32 v79, 0
	v_mov_b32_e32 v78, 0
	v_mov_b32_e32 v53, 0
	v_mov_b32_e32 v52, 0
	v_mov_b32_e32 v47, 0
	v_mov_b32_e32 v46, 0
	v_mov_b32_e32 v49, 0
	v_mov_b32_e32 v48, 0
	v_mov_b32_e32 v77, 0
	v_mov_b32_e32 v76, 0
	v_mov_b32_e32 v45, 0
	v_mov_b32_e32 v44, 0
	v_mov_b32_e32 v75, 0
	v_mov_b32_e32 v74, 0
	v_mov_b32_e32 v43, 0
	v_mov_b32_e32 v42, 0
	v_mov_b32_e32 v69, 0
	v_mov_b32_e32 v68, 0
	v_mov_b32_e32 v41, 0
	v_mov_b32_e32 v40, 0
	v_mov_b32_e32 v67, 0
	v_mov_b32_e32 v66, 0
	v_mov_b32_e32 v39, 0
	v_mov_b32_e32 v38, 0
	v_mov_b32_e32 v65, 0
	v_mov_b32_e32 v64, 0
	v_mov_b32_e32 v37, 0
	v_mov_b32_e32 v36, 0
	v_mov_b32_e32 v63, 0
	v_mov_b32_e32 v62, 0
	v_mov_b32_e32 v35, 0
	v_mov_b32_e32 v34, 0
	v_mov_b32_e32 v61, 0
	v_mov_b32_e32 v60, 0
	v_mov_b32_e32 v33, 0
	v_mov_b32_e32 v32, 0
	v_mov_b32_e32 v59, 0
	v_mov_b32_e32 v58, 0
	v_mov_b32_e32 v31, 0
	v_mov_b32_e32 v30, 0
	v_mov_b32_e32 v57, 0
	v_mov_b32_e32 v56, 0
	v_mov_b32_e32 v29, 0
	v_mov_b32_e32 v28, 0
	v_mov_b32_e32 v55, 0
	v_mov_b32_e32 v54, 0
	v_mov_b32_e32 v27, 0
	v_mov_b32_e32 v26, 0
	v_mov_b32_e32 v51, 0
	v_mov_b32_e32 v50, 0
	v_mov_b32_e32 v25, 0
	v_mov_b32_e32 v24, 0
	s_cbranch_vccnz .LBB0_718

.LBB0_720:
	s_andn2_b64 vcc, exec, s[10:11]
	v_mov_b32_e32 v254, 0xbfb8aa3b
	v_mov_b32_e32 v255, 1.0
	v_lshl_or_b32 v190, s57, 7, v171
	v_ashrrev_i32_e32 v191, 31, v190
	v_mov_b64_e32 v[192:193], s[24:25]
	v_lshlrev_b64 v[190:191], 1, v[190:191]
	v_pk_mul_f32 v[160:161], v[228:229], v[160:161]
	v_pk_mul_f32 v[100:101], v[236:237], v[100:101]
	v_pk_mul_f32 v[160:161], v[160:161], v[244:245] op_sel_hi:[1,0]
	v_pk_mul_f32 v[100:101], v[100:101], v[244:245] op_sel_hi:[1,0]
	v_pk_mul_f32 v[162:163], v[230:231], v[162:163]
	v_pk_mul_f32 v[120:121], v[238:239], v[120:121]
	v_pk_mul_f32 v[162:163], v[162:163], v[244:245] op_sel_hi:[1,0]
	v_pk_mul_f32 v[120:121], v[120:121], v[244:245] op_sel_hi:[1,0]
	v_pk_mul_f32 v[146:147], v[232:233], v[146:147]
	v_pk_mul_f32 v[98:99], v[240:241], v[98:99]
	v_pk_mul_f32 v[146:147], v[146:147], v[244:245] op_sel_hi:[1,0]
	v_pk_mul_f32 v[98:99], v[98:99], v[244:245] op_sel_hi:[1,0]
	v_pk_mul_f32 v[158:159], v[234:235], v[158:159]
	v_pk_mul_f32 v[116:117], v[242:243], v[116:117]
	v_pk_mul_f32 v[158:159], v[158:159], v[244:245] op_sel_hi:[1,0]
	v_pk_mul_f32 v[116:117], v[116:117], v[244:245] op_sel_hi:[1,0]
	v_pk_mul_f32 v[178:179], v[160:161], v[254:255] op_sel_hi:[1,0]
	v_pk_mul_f32 v[180:181], v[162:163], v[254:255] op_sel_hi:[1,0]
	v_pk_mul_f32 v[182:183], v[146:147], v[254:255] op_sel_hi:[1,0]
	v_pk_mul_f32 v[184:185], v[158:159], v[254:255] op_sel_hi:[1,0]
	v_exp_f32_e32 v178, v178
	v_exp_f32_e32 v179, v179
	v_exp_f32_e32 v180, v180
	v_exp_f32_e32 v181, v181
	v_exp_f32_e32 v182, v182
	v_exp_f32_e32 v183, v183
	v_exp_f32_e32 v184, v184
	v_exp_f32_e32 v185, v185
	s_waitcnt vmcnt(0)
	v_add_u32_e32 v196, 0x0, v223
	v_mad_i64_i32 v[194:195], s[20:21], v196, s56, v[192:193]
	v_pk_add_f32 v[178:179], v[178:179], v[254:255] op_sel:[0,1] op_sel_hi:[1,1]
	v_pk_add_f32 v[180:181], v[180:181], v[254:255] op_sel:[0,1] op_sel_hi:[1,1]
	v_pk_add_f32 v[182:183], v[182:183], v[254:255] op_sel:[0,1] op_sel_hi:[1,1]
	v_pk_add_f32 v[184:185], v[184:185], v[254:255] op_sel:[0,1] op_sel_hi:[1,1]
	v_rcp_f32_e32 v178, v178
	v_rcp_f32_e32 v179, v179
	v_rcp_f32_e32 v180, v180
	v_rcp_f32_e32 v181, v181
	v_rcp_f32_e32 v182, v182
	v_rcp_f32_e32 v183, v183
	v_rcp_f32_e32 v184, v184
	v_rcp_f32_e32 v185, v185
	v_lshl_add_u64 v[194:195], v[194:195], 0, v[190:191]
	v_pk_mul_f32 v[178:179], v[160:161], v[178:179]
	v_pk_mul_f32 v[180:181], v[162:163], v[180:181]
	v_pk_mul_f32 v[182:183], v[146:147], v[182:183]
	v_pk_mul_f32 v[184:185], v[158:159], v[184:185]
	v_pk_mul_f32 v[178:179], v[100:101], v[178:179]
	v_pk_mul_f32 v[180:181], v[120:121], v[180:181]
	v_pk_mul_f32 v[182:183], v[98:99], v[182:183]
	v_pk_mul_f32 v[184:185], v[116:117], v[184:185]
	v_cvt_pk_bf16_f32 v186, v178, v179
	v_cvt_pk_bf16_f32 v187, v180, v181
	v_cvt_pk_bf16_f32 v188, v182, v183
	v_cvt_pk_bf16_f32 v189, v184, v185
	global_store_dwordx4 v[194:195], v[186:189], off
	v_pk_mul_f32 v[144:145], v[228:229], v[144:145]
	v_pk_mul_f32 v[96:97], v[236:237], v[96:97]
	v_pk_mul_f32 v[144:145], v[144:145], v[244:245] op_sel:[0,1] op_sel_hi:[1,1]
	v_pk_mul_f32 v[96:97], v[96:97], v[244:245] op_sel:[0,1] op_sel_hi:[1,1]
	v_pk_mul_f32 v[156:157], v[230:231], v[156:157]
	v_pk_mul_f32 v[114:115], v[238:239], v[114:115]
	v_pk_mul_f32 v[156:157], v[156:157], v[244:245] op_sel:[0,1] op_sel_hi:[1,1]
	v_pk_mul_f32 v[114:115], v[114:115], v[244:245] op_sel:[0,1] op_sel_hi:[1,1]
	v_pk_mul_f32 v[140:141], v[232:233], v[140:141]
	v_pk_mul_f32 v[94:95], v[240:241], v[94:95]
	v_pk_mul_f32 v[140:141], v[140:141], v[244:245] op_sel:[0,1] op_sel_hi:[1,1]
	v_pk_mul_f32 v[94:95], v[94:95], v[244:245] op_sel:[0,1] op_sel_hi:[1,1]
	v_pk_mul_f32 v[154:155], v[234:235], v[154:155]
	v_pk_mul_f32 v[112:113], v[242:243], v[112:113]
	v_pk_mul_f32 v[154:155], v[154:155], v[244:245] op_sel:[0,1] op_sel_hi:[1,1]
	v_pk_mul_f32 v[112:113], v[112:113], v[244:245] op_sel:[0,1] op_sel_hi:[1,1]
	v_pk_mul_f32 v[178:179], v[144:145], v[254:255] op_sel_hi:[1,0]
	v_pk_mul_f32 v[180:181], v[156:157], v[254:255] op_sel_hi:[1,0]
	v_pk_mul_f32 v[182:183], v[140:141], v[254:255] op_sel_hi:[1,0]
	v_pk_mul_f32 v[184:185], v[154:155], v[254:255] op_sel_hi:[1,0]
	v_exp_f32_e32 v178, v178
	v_exp_f32_e32 v179, v179
	v_exp_f32_e32 v180, v180
	v_exp_f32_e32 v181, v181
	v_exp_f32_e32 v182, v182
	v_exp_f32_e32 v183, v183
	v_exp_f32_e32 v184, v184
	v_exp_f32_e32 v185, v185
	v_add_u32_e32 v196, 0x10, v223
	v_mad_i64_i32 v[194:195], s[20:21], v196, s56, v[192:193]
	v_pk_add_f32 v[178:179], v[178:179], v[254:255] op_sel:[0,1] op_sel_hi:[1,1]
	v_pk_add_f32 v[180:181], v[180:181], v[254:255] op_sel:[0,1] op_sel_hi:[1,1]
	v_pk_add_f32 v[182:183], v[182:183], v[254:255] op_sel:[0,1] op_sel_hi:[1,1]
	v_pk_add_f32 v[184:185], v[184:185], v[254:255] op_sel:[0,1] op_sel_hi:[1,1]
	v_rcp_f32_e32 v178, v178
	v_rcp_f32_e32 v179, v179
	v_rcp_f32_e32 v180, v180
	v_rcp_f32_e32 v181, v181
	v_rcp_f32_e32 v182, v182
	v_rcp_f32_e32 v183, v183
	v_rcp_f32_e32 v184, v184
	v_rcp_f32_e32 v185, v185
	v_lshl_add_u64 v[194:195], v[194:195], 0, v[190:191]
	v_pk_mul_f32 v[178:179], v[144:145], v[178:179]
	v_pk_mul_f32 v[180:181], v[156:157], v[180:181]
	v_pk_mul_f32 v[182:183], v[140:141], v[182:183]
	v_pk_mul_f32 v[184:185], v[154:155], v[184:185]
	v_pk_mul_f32 v[178:179], v[96:97], v[178:179]
	v_pk_mul_f32 v[180:181], v[114:115], v[180:181]
	v_pk_mul_f32 v[182:183], v[94:95], v[182:183]
	v_pk_mul_f32 v[184:185], v[112:113], v[184:185]
	v_cvt_pk_bf16_f32 v198, v178, v179
	v_cvt_pk_bf16_f32 v199, v180, v181
	v_cvt_pk_bf16_f32 v200, v182, v183
	v_cvt_pk_bf16_f32 v201, v184, v185
	global_store_dwordx4 v[194:195], v[198:201], off
	v_pk_mul_f32 v[126:127], v[228:229], v[126:127]
	v_pk_mul_f32 v[92:93], v[236:237], v[92:93]
	v_pk_mul_f32 v[126:127], v[126:127], v[246:247] op_sel_hi:[1,0]
	v_pk_mul_f32 v[92:93], v[92:93], v[246:247] op_sel_hi:[1,0]
	v_pk_mul_f32 v[152:153], v[230:231], v[152:153]
	v_pk_mul_f32 v[110:111], v[238:239], v[110:111]
	v_pk_mul_f32 v[152:153], v[152:153], v[246:247] op_sel_hi:[1,0]
	v_pk_mul_f32 v[110:111], v[110:111], v[246:247] op_sel_hi:[1,0]
	v_pk_mul_f32 v[124:125], v[232:233], v[124:125]
	v_pk_mul_f32 v[90:91], v[240:241], v[90:91]
	v_pk_mul_f32 v[124:125], v[124:125], v[246:247] op_sel_hi:[1,0]
	v_pk_mul_f32 v[90:91], v[90:91], v[246:247] op_sel_hi:[1,0]
	v_pk_mul_f32 v[150:151], v[234:235], v[150:151]
	v_pk_mul_f32 v[108:109], v[242:243], v[108:109]
	v_pk_mul_f32 v[150:151], v[150:151], v[246:247] op_sel_hi:[1,0]
	v_pk_mul_f32 v[108:109], v[108:109], v[246:247] op_sel_hi:[1,0]
	v_pk_mul_f32 v[178:179], v[126:127], v[254:255] op_sel_hi:[1,0]
	v_pk_mul_f32 v[180:181], v[152:153], v[254:255] op_sel_hi:[1,0]
	v_pk_mul_f32 v[182:183], v[124:125], v[254:255] op_sel_hi:[1,0]
	v_pk_mul_f32 v[184:185], v[150:151], v[254:255] op_sel_hi:[1,0]
	v_exp_f32_e32 v178, v178
	v_exp_f32_e32 v179, v179
	v_exp_f32_e32 v180, v180
	v_exp_f32_e32 v181, v181
	v_exp_f32_e32 v182, v182
	v_exp_f32_e32 v183, v183
	v_exp_f32_e32 v184, v184
	v_exp_f32_e32 v185, v185
	v_add_u32_e32 v196, 0x20, v223
	v_mad_i64_i32 v[194:195], s[20:21], v196, s56, v[192:193]
	v_pk_add_f32 v[178:179], v[178:179], v[254:255] op_sel:[0,1] op_sel_hi:[1,1]
	v_pk_add_f32 v[180:181], v[180:181], v[254:255] op_sel:[0,1] op_sel_hi:[1,1]
	v_pk_add_f32 v[182:183], v[182:183], v[254:255] op_sel:[0,1] op_sel_hi:[1,1]
	v_pk_add_f32 v[184:185], v[184:185], v[254:255] op_sel:[0,1] op_sel_hi:[1,1]
	v_rcp_f32_e32 v178, v178
	v_rcp_f32_e32 v179, v179
	v_rcp_f32_e32 v180, v180
	v_rcp_f32_e32 v181, v181
	v_rcp_f32_e32 v182, v182
	v_rcp_f32_e32 v183, v183
	v_rcp_f32_e32 v184, v184
	v_rcp_f32_e32 v185, v185
	v_lshl_add_u64 v[194:195], v[194:195], 0, v[190:191]
	v_pk_mul_f32 v[178:179], v[126:127], v[178:179]
	v_pk_mul_f32 v[180:181], v[152:153], v[180:181]
	v_pk_mul_f32 v[182:183], v[124:125], v[182:183]
	v_pk_mul_f32 v[184:185], v[150:151], v[184:185]
	v_pk_mul_f32 v[178:179], v[92:93], v[178:179]
	v_pk_mul_f32 v[180:181], v[110:111], v[180:181]
	v_pk_mul_f32 v[182:183], v[90:91], v[182:183]
	v_pk_mul_f32 v[184:185], v[108:109], v[184:185]
	v_cvt_pk_bf16_f32 v186, v178, v179
	v_cvt_pk_bf16_f32 v187, v180, v181
	v_cvt_pk_bf16_f32 v188, v182, v183
	v_cvt_pk_bf16_f32 v189, v184, v185
	global_store_dwordx4 v[194:195], v[186:189], off
	v_pk_mul_f32 v[122:123], v[228:229], v[122:123]
	v_pk_mul_f32 v[88:89], v[236:237], v[88:89]
	v_pk_mul_f32 v[122:123], v[122:123], v[246:247] op_sel:[0,1] op_sel_hi:[1,1]
	v_pk_mul_f32 v[88:89], v[88:89], v[246:247] op_sel:[0,1] op_sel_hi:[1,1]
	v_pk_mul_f32 v[148:149], v[230:231], v[148:149]
	v_pk_mul_f32 v[106:107], v[238:239], v[106:107]
	v_pk_mul_f32 v[148:149], v[148:149], v[246:247] op_sel:[0,1] op_sel_hi:[1,1]
	v_pk_mul_f32 v[106:107], v[106:107], v[246:247] op_sel:[0,1] op_sel_hi:[1,1]
	v_pk_mul_f32 v[118:119], v[232:233], v[118:119]
	v_pk_mul_f32 v[86:87], v[240:241], v[86:87]
	v_pk_mul_f32 v[118:119], v[118:119], v[246:247] op_sel:[0,1] op_sel_hi:[1,1]
	v_pk_mul_f32 v[86:87], v[86:87], v[246:247] op_sel:[0,1] op_sel_hi:[1,1]
	v_pk_mul_f32 v[142:143], v[234:235], v[142:143]
	v_pk_mul_f32 v[104:105], v[242:243], v[104:105]
	v_pk_mul_f32 v[142:143], v[142:143], v[246:247] op_sel:[0,1] op_sel_hi:[1,1]
	v_pk_mul_f32 v[104:105], v[104:105], v[246:247] op_sel:[0,1] op_sel_hi:[1,1]
	v_pk_mul_f32 v[178:179], v[122:123], v[254:255] op_sel_hi:[1,0]
	v_pk_mul_f32 v[180:181], v[148:149], v[254:255] op_sel_hi:[1,0]
	v_pk_mul_f32 v[182:183], v[118:119], v[254:255] op_sel_hi:[1,0]
	v_pk_mul_f32 v[184:185], v[142:143], v[254:255] op_sel_hi:[1,0]
	v_exp_f32_e32 v178, v178
	v_exp_f32_e32 v179, v179
	v_exp_f32_e32 v180, v180
	v_exp_f32_e32 v181, v181
	v_exp_f32_e32 v182, v182
	v_exp_f32_e32 v183, v183
	v_exp_f32_e32 v184, v184
	v_exp_f32_e32 v185, v185
	v_add_u32_e32 v196, 0x30, v223
	v_mad_i64_i32 v[194:195], s[20:21], v196, s56, v[192:193]
	v_pk_add_f32 v[178:179], v[178:179], v[254:255] op_sel:[0,1] op_sel_hi:[1,1]
	v_pk_add_f32 v[180:181], v[180:181], v[254:255] op_sel:[0,1] op_sel_hi:[1,1]
	v_pk_add_f32 v[182:183], v[182:183], v[254:255] op_sel:[0,1] op_sel_hi:[1,1]
	v_pk_add_f32 v[184:185], v[184:185], v[254:255] op_sel:[0,1] op_sel_hi:[1,1]
	v_rcp_f32_e32 v178, v178
	v_rcp_f32_e32 v179, v179
	v_rcp_f32_e32 v180, v180
	v_rcp_f32_e32 v181, v181
	v_rcp_f32_e32 v182, v182
	v_rcp_f32_e32 v183, v183
	v_rcp_f32_e32 v184, v184
	v_rcp_f32_e32 v185, v185
	v_lshl_add_u64 v[194:195], v[194:195], 0, v[190:191]
	v_pk_mul_f32 v[178:179], v[122:123], v[178:179]
	v_pk_mul_f32 v[180:181], v[148:149], v[180:181]
	v_pk_mul_f32 v[182:183], v[118:119], v[182:183]
	v_pk_mul_f32 v[184:185], v[142:143], v[184:185]
	v_pk_mul_f32 v[178:179], v[88:89], v[178:179]
	v_pk_mul_f32 v[180:181], v[106:107], v[180:181]
	v_pk_mul_f32 v[182:183], v[86:87], v[182:183]
	v_pk_mul_f32 v[184:185], v[104:105], v[184:185]
	v_cvt_pk_bf16_f32 v198, v178, v179
	v_cvt_pk_bf16_f32 v199, v180, v181
	v_cvt_pk_bf16_f32 v200, v182, v183
	v_cvt_pk_bf16_f32 v201, v184, v185
	global_store_dwordx4 v[194:195], v[198:201], off
	v_pk_mul_f32 v[84:85], v[228:229], v[84:85]
	v_pk_mul_f32 v[38:39], v[236:237], v[38:39]
	v_pk_mul_f32 v[84:85], v[84:85], v[248:249] op_sel_hi:[1,0]
	v_pk_mul_f32 v[38:39], v[38:39], v[248:249] op_sel_hi:[1,0]
	v_pk_mul_f32 v[102:103], v[230:231], v[102:103]
	v_pk_mul_f32 v[66:67], v[238:239], v[66:67]
	v_pk_mul_f32 v[102:103], v[102:103], v[248:249] op_sel_hi:[1,0]
	v_pk_mul_f32 v[66:67], v[66:67], v[248:249] op_sel_hi:[1,0]
	v_pk_mul_f32 v[72:73], v[232:233], v[72:73]
	v_pk_mul_f32 v[36:37], v[240:241], v[36:37]
	v_pk_mul_f32 v[72:73], v[72:73], v[248:249] op_sel_hi:[1,0]
	v_pk_mul_f32 v[36:37], v[36:37], v[248:249] op_sel_hi:[1,0]
	v_pk_mul_f32 v[82:83], v[234:235], v[82:83]
	v_pk_mul_f32 v[64:65], v[242:243], v[64:65]
	v_pk_mul_f32 v[82:83], v[82:83], v[248:249] op_sel_hi:[1,0]
	v_pk_mul_f32 v[64:65], v[64:65], v[248:249] op_sel_hi:[1,0]
	v_pk_mul_f32 v[178:179], v[84:85], v[254:255] op_sel_hi:[1,0]
	v_pk_mul_f32 v[180:181], v[102:103], v[254:255] op_sel_hi:[1,0]
	v_pk_mul_f32 v[182:183], v[72:73], v[254:255] op_sel_hi:[1,0]
	v_pk_mul_f32 v[184:185], v[82:83], v[254:255] op_sel_hi:[1,0]
	v_exp_f32_e32 v178, v178
	v_exp_f32_e32 v179, v179
	v_exp_f32_e32 v180, v180
	v_exp_f32_e32 v181, v181
	v_exp_f32_e32 v182, v182
	v_exp_f32_e32 v183, v183
	v_exp_f32_e32 v184, v184
	v_exp_f32_e32 v185, v185
	v_add_u32_e32 v196, 0x80, v223
	v_mad_i64_i32 v[194:195], s[20:21], v196, s56, v[192:193]
	v_pk_add_f32 v[178:179], v[178:179], v[254:255] op_sel:[0,1] op_sel_hi:[1,1]
	v_pk_add_f32 v[180:181], v[180:181], v[254:255] op_sel:[0,1] op_sel_hi:[1,1]
	v_pk_add_f32 v[182:183], v[182:183], v[254:255] op_sel:[0,1] op_sel_hi:[1,1]
	v_pk_add_f32 v[184:185], v[184:185], v[254:255] op_sel:[0,1] op_sel_hi:[1,1]
	v_rcp_f32_e32 v178, v178
	v_rcp_f32_e32 v179, v179
	v_rcp_f32_e32 v180, v180
	v_rcp_f32_e32 v181, v181
	v_rcp_f32_e32 v182, v182
	v_rcp_f32_e32 v183, v183
	v_rcp_f32_e32 v184, v184
	v_rcp_f32_e32 v185, v185
	v_lshl_add_u64 v[194:195], v[194:195], 0, v[190:191]
	v_pk_mul_f32 v[178:179], v[84:85], v[178:179]
	v_pk_mul_f32 v[180:181], v[102:103], v[180:181]
	v_pk_mul_f32 v[182:183], v[72:73], v[182:183]
	v_pk_mul_f32 v[184:185], v[82:83], v[184:185]
	v_pk_mul_f32 v[178:179], v[38:39], v[178:179]
	v_pk_mul_f32 v[180:181], v[66:67], v[180:181]
	v_pk_mul_f32 v[182:183], v[36:37], v[182:183]
	v_pk_mul_f32 v[184:185], v[64:65], v[184:185]
	v_cvt_pk_bf16_f32 v186, v178, v179
	v_cvt_pk_bf16_f32 v187, v180, v181
	v_cvt_pk_bf16_f32 v188, v182, v183
	v_cvt_pk_bf16_f32 v189, v184, v185
	global_store_dwordx4 v[194:195], v[186:189], off
	v_pk_mul_f32 v[70:71], v[228:229], v[70:71]
	v_pk_mul_f32 v[34:35], v[236:237], v[34:35]
	v_pk_mul_f32 v[70:71], v[70:71], v[248:249] op_sel:[0,1] op_sel_hi:[1,1]
	v_pk_mul_f32 v[34:35], v[34:35], v[248:249] op_sel:[0,1] op_sel_hi:[1,1]
	v_pk_mul_f32 v[80:81], v[230:231], v[80:81]
	v_pk_mul_f32 v[62:63], v[238:239], v[62:63]
	v_pk_mul_f32 v[80:81], v[80:81], v[248:249] op_sel:[0,1] op_sel_hi:[1,1]
	v_pk_mul_f32 v[62:63], v[62:63], v[248:249] op_sel:[0,1] op_sel_hi:[1,1]
	v_pk_mul_f32 v[52:53], v[232:233], v[52:53]
	v_pk_mul_f32 v[32:33], v[240:241], v[32:33]
	v_pk_mul_f32 v[52:53], v[52:53], v[248:249] op_sel:[0,1] op_sel_hi:[1,1]
	v_pk_mul_f32 v[32:33], v[32:33], v[248:249] op_sel:[0,1] op_sel_hi:[1,1]
	v_pk_mul_f32 v[78:79], v[234:235], v[78:79]
	v_pk_mul_f32 v[60:61], v[242:243], v[60:61]
	v_pk_mul_f32 v[78:79], v[78:79], v[248:249] op_sel:[0,1] op_sel_hi:[1,1]
	v_pk_mul_f32 v[60:61], v[60:61], v[248:249] op_sel:[0,1] op_sel_hi:[1,1]
	v_pk_mul_f32 v[178:179], v[70:71], v[254:255] op_sel_hi:[1,0]
	v_pk_mul_f32 v[180:181], v[80:81], v[254:255] op_sel_hi:[1,0]
	v_pk_mul_f32 v[182:183], v[52:53], v[254:255] op_sel_hi:[1,0]
	v_pk_mul_f32 v[184:185], v[78:79], v[254:255] op_sel_hi:[1,0]
	v_exp_f32_e32 v178, v178
	v_exp_f32_e32 v179, v179
	v_exp_f32_e32 v180, v180
	v_exp_f32_e32 v181, v181
	v_exp_f32_e32 v182, v182
	v_exp_f32_e32 v183, v183
	v_exp_f32_e32 v184, v184
	v_exp_f32_e32 v185, v185
	v_add_u32_e32 v196, 0x90, v223
	v_mad_i64_i32 v[194:195], s[20:21], v196, s56, v[192:193]
	v_pk_add_f32 v[178:179], v[178:179], v[254:255] op_sel:[0,1] op_sel_hi:[1,1]
	v_pk_add_f32 v[180:181], v[180:181], v[254:255] op_sel:[0,1] op_sel_hi:[1,1]
	v_pk_add_f32 v[182:183], v[182:183], v[254:255] op_sel:[0,1] op_sel_hi:[1,1]
	v_pk_add_f32 v[184:185], v[184:185], v[254:255] op_sel:[0,1] op_sel_hi:[1,1]
	v_rcp_f32_e32 v178, v178
	v_rcp_f32_e32 v179, v179
	v_rcp_f32_e32 v180, v180
	v_rcp_f32_e32 v181, v181
	v_rcp_f32_e32 v182, v182
	v_rcp_f32_e32 v183, v183
	v_rcp_f32_e32 v184, v184
	v_rcp_f32_e32 v185, v185
	v_lshl_add_u64 v[194:195], v[194:195], 0, v[190:191]
	v_pk_mul_f32 v[178:179], v[70:71], v[178:179]
	v_pk_mul_f32 v[180:181], v[80:81], v[180:181]
	v_pk_mul_f32 v[182:183], v[52:53], v[182:183]
	v_pk_mul_f32 v[184:185], v[78:79], v[184:185]
	v_pk_mul_f32 v[178:179], v[34:35], v[178:179]
	v_pk_mul_f32 v[180:181], v[62:63], v[180:181]
	v_pk_mul_f32 v[182:183], v[32:33], v[182:183]
	v_pk_mul_f32 v[184:185], v[60:61], v[184:185]
	v_cvt_pk_bf16_f32 v198, v178, v179
	v_cvt_pk_bf16_f32 v199, v180, v181
	v_cvt_pk_bf16_f32 v200, v182, v183
	v_cvt_pk_bf16_f32 v201, v184, v185
	global_store_dwordx4 v[194:195], v[198:201], off
	v_pk_mul_f32 v[48:49], v[228:229], v[48:49]
	v_pk_mul_f32 v[30:31], v[236:237], v[30:31]
	v_pk_mul_f32 v[48:49], v[48:49], v[250:251] op_sel_hi:[1,0]
	v_pk_mul_f32 v[30:31], v[30:31], v[250:251] op_sel_hi:[1,0]
	v_pk_mul_f32 v[46:47], v[230:231], v[46:47]
	v_pk_mul_f32 v[58:59], v[238:239], v[58:59]
	v_pk_mul_f32 v[46:47], v[46:47], v[250:251] op_sel_hi:[1,0]
	v_pk_mul_f32 v[58:59], v[58:59], v[250:251] op_sel_hi:[1,0]
	v_pk_mul_f32 v[44:45], v[232:233], v[44:45]
	v_pk_mul_f32 v[28:29], v[240:241], v[28:29]
	v_pk_mul_f32 v[44:45], v[44:45], v[250:251] op_sel_hi:[1,0]
	v_pk_mul_f32 v[28:29], v[28:29], v[250:251] op_sel_hi:[1,0]
	v_pk_mul_f32 v[76:77], v[234:235], v[76:77]
	v_pk_mul_f32 v[56:57], v[242:243], v[56:57]
	v_pk_mul_f32 v[76:77], v[76:77], v[250:251] op_sel_hi:[1,0]
	v_pk_mul_f32 v[56:57], v[56:57], v[250:251] op_sel_hi:[1,0]
	v_pk_mul_f32 v[178:179], v[48:49], v[254:255] op_sel_hi:[1,0]
	v_pk_mul_f32 v[180:181], v[46:47], v[254:255] op_sel_hi:[1,0]
	v_pk_mul_f32 v[182:183], v[44:45], v[254:255] op_sel_hi:[1,0]
	v_pk_mul_f32 v[184:185], v[76:77], v[254:255] op_sel_hi:[1,0]
	v_exp_f32_e32 v178, v178
	v_exp_f32_e32 v179, v179
	v_exp_f32_e32 v180, v180
	v_exp_f32_e32 v181, v181
	v_exp_f32_e32 v182, v182
	v_exp_f32_e32 v183, v183
	v_exp_f32_e32 v184, v184
	v_exp_f32_e32 v185, v185
	v_add_u32_e32 v196, 0xa0, v223
	v_mad_i64_i32 v[194:195], s[20:21], v196, s56, v[192:193]
	v_pk_add_f32 v[178:179], v[178:179], v[254:255] op_sel:[0,1] op_sel_hi:[1,1]
	v_pk_add_f32 v[180:181], v[180:181], v[254:255] op_sel:[0,1] op_sel_hi:[1,1]
	v_pk_add_f32 v[182:183], v[182:183], v[254:255] op_sel:[0,1] op_sel_hi:[1,1]
	v_pk_add_f32 v[184:185], v[184:185], v[254:255] op_sel:[0,1] op_sel_hi:[1,1]
	v_rcp_f32_e32 v178, v178
	v_rcp_f32_e32 v179, v179
	v_rcp_f32_e32 v180, v180
	v_rcp_f32_e32 v181, v181
	v_rcp_f32_e32 v182, v182
	v_rcp_f32_e32 v183, v183
	v_rcp_f32_e32 v184, v184
	v_rcp_f32_e32 v185, v185
	v_lshl_add_u64 v[194:195], v[194:195], 0, v[190:191]
	v_pk_mul_f32 v[178:179], v[48:49], v[178:179]
	v_pk_mul_f32 v[180:181], v[46:47], v[180:181]
	v_pk_mul_f32 v[182:183], v[44:45], v[182:183]
	v_pk_mul_f32 v[184:185], v[76:77], v[184:185]
	v_pk_mul_f32 v[178:179], v[30:31], v[178:179]
	v_pk_mul_f32 v[180:181], v[58:59], v[180:181]
	v_pk_mul_f32 v[182:183], v[28:29], v[182:183]
	v_pk_mul_f32 v[184:185], v[56:57], v[184:185]
	v_cvt_pk_bf16_f32 v186, v178, v179
	v_cvt_pk_bf16_f32 v187, v180, v181
	v_cvt_pk_bf16_f32 v188, v182, v183
	v_cvt_pk_bf16_f32 v189, v184, v185
	global_store_dwordx4 v[194:195], v[186:189], off
	v_pk_mul_f32 v[42:43], v[228:229], v[42:43]
	v_pk_mul_f32 v[26:27], v[236:237], v[26:27]
	v_pk_mul_f32 v[42:43], v[42:43], v[250:251] op_sel:[0,1] op_sel_hi:[1,1]
	v_pk_mul_f32 v[26:27], v[26:27], v[250:251] op_sel:[0,1] op_sel_hi:[1,1]
	v_pk_mul_f32 v[74:75], v[230:231], v[74:75]
	v_pk_mul_f32 v[54:55], v[238:239], v[54:55]
	v_pk_mul_f32 v[74:75], v[74:75], v[250:251] op_sel:[0,1] op_sel_hi:[1,1]
	v_pk_mul_f32 v[54:55], v[54:55], v[250:251] op_sel:[0,1] op_sel_hi:[1,1]
	v_pk_mul_f32 v[40:41], v[232:233], v[40:41]
	v_pk_mul_f32 v[24:25], v[240:241], v[24:25]
	v_pk_mul_f32 v[40:41], v[40:41], v[250:251] op_sel:[0,1] op_sel_hi:[1,1]
	v_pk_mul_f32 v[24:25], v[24:25], v[250:251] op_sel:[0,1] op_sel_hi:[1,1]
	v_pk_mul_f32 v[68:69], v[234:235], v[68:69]
	v_pk_mul_f32 v[50:51], v[242:243], v[50:51]
	v_pk_mul_f32 v[68:69], v[68:69], v[250:251] op_sel:[0,1] op_sel_hi:[1,1]
	v_pk_mul_f32 v[50:51], v[50:51], v[250:251] op_sel:[0,1] op_sel_hi:[1,1]
	v_pk_mul_f32 v[178:179], v[42:43], v[254:255] op_sel_hi:[1,0]
	v_pk_mul_f32 v[180:181], v[74:75], v[254:255] op_sel_hi:[1,0]
	v_pk_mul_f32 v[182:183], v[40:41], v[254:255] op_sel_hi:[1,0]
	v_pk_mul_f32 v[184:185], v[68:69], v[254:255] op_sel_hi:[1,0]
	v_exp_f32_e32 v178, v178
	v_exp_f32_e32 v179, v179
	v_exp_f32_e32 v180, v180
	v_exp_f32_e32 v181, v181
	v_exp_f32_e32 v182, v182
	v_exp_f32_e32 v183, v183
	v_exp_f32_e32 v184, v184
	v_exp_f32_e32 v185, v185
	v_add_u32_e32 v196, 0xb0, v223
	v_mad_i64_i32 v[194:195], s[20:21], v196, s56, v[192:193]
	v_pk_add_f32 v[178:179], v[178:179], v[254:255] op_sel:[0,1] op_sel_hi:[1,1]
	v_pk_add_f32 v[180:181], v[180:181], v[254:255] op_sel:[0,1] op_sel_hi:[1,1]
	v_pk_add_f32 v[182:183], v[182:183], v[254:255] op_sel:[0,1] op_sel_hi:[1,1]
	v_pk_add_f32 v[184:185], v[184:185], v[254:255] op_sel:[0,1] op_sel_hi:[1,1]
	v_rcp_f32_e32 v178, v178
	v_rcp_f32_e32 v179, v179
	v_rcp_f32_e32 v180, v180
	v_rcp_f32_e32 v181, v181
	v_rcp_f32_e32 v182, v182
	v_rcp_f32_e32 v183, v183
	v_rcp_f32_e32 v184, v184
	v_rcp_f32_e32 v185, v185
	v_lshl_add_u64 v[194:195], v[194:195], 0, v[190:191]
	v_pk_mul_f32 v[178:179], v[42:43], v[178:179]
	v_pk_mul_f32 v[180:181], v[74:75], v[180:181]
	v_pk_mul_f32 v[182:183], v[40:41], v[182:183]
	v_pk_mul_f32 v[184:185], v[68:69], v[184:185]
	v_pk_mul_f32 v[178:179], v[26:27], v[178:179]
	v_pk_mul_f32 v[180:181], v[54:55], v[180:181]
	v_pk_mul_f32 v[182:183], v[24:25], v[182:183]
	v_pk_mul_f32 v[184:185], v[50:51], v[184:185]
	v_cvt_pk_bf16_f32 v198, v178, v179
	v_cvt_pk_bf16_f32 v199, v180, v181
	v_cvt_pk_bf16_f32 v200, v182, v183
	v_cvt_pk_bf16_f32 v201, v184, v185
	global_store_dwordx4 v[194:195], v[198:201], off
	s_cbranch_vccnz .LBB0_711
	s_barrier
	s_branch .LBB0_711
